# mout: the P-store drain wait before GEMM2 removed (GEMM2 does not read P; its own counted waits and final vmcnt(0)+barrier complete the stores before GEMM3 reads them); on top of v64
# baseline (speedup 1.0000x reference)
.LBB0_655:
	s_or_b64 exec, exec, s[26:27]
	s_lshl_b64 s[0:1], s[0:1], 1
	s_add_u32 s26, s45, s0
	s_addc_u32 s27, s52, s1
	v_mov_b32_e32 v14, v182
	s_nop 0
	s_waitcnt lgkmcnt(0)
	s_barrier
	s_nop 0
	v_bfe_i32 v2, v14, 27, 1
	v_lshlrev_b32_e32 v1, 4, v14
	v_lshrrev_b32_e32 v2, 22, v2
	v_add_u32_e32 v2, v1, v2
	v_and_b32_e32 v2, 0xfffffc00, v2
	v_sub_u32_e32 v2, v1, v2
	v_ashrrev_i32_e32 v0, 31, v14
	v_lshrrev_b32_e32 v3, 4, v2
	v_lshrrev_b32_e32 v0, 26, v0
	v_bitop3_b32 v3, v3, v2, 32 bitop3:0x6c
	v_ashrrev_i32_e32 v2, 31, v2
	v_add_u32_e32 v0, v14, v0
	v_lshrrev_b32_e32 v2, 26, v2
	v_ashrrev_i32_e32 v0, 6, v0
	v_add_u32_e32 v2, v3, v2
	v_lshlrev_b32_e32 v4, 3, v0
	v_ashrrev_i32_e32 v2, 6, v2
	v_and_b32_e32 v4, -16, v4
	v_mul_i32_i24_e32 v5, 64, v2
	v_add_u32_e32 v4, v2, v4
	v_sub_u32_e32 v3, v3, v5
	v_lshlrev_b32_e32 v0, 5, v0
	v_ashrrev_i16_sdwa v3, v184, sext(v3) dst_sel:DWORD dst_unused:UNUSED_PAD src0_sel:DWORD src1_sel:BYTE_0
	v_lshlrev_b32_e32 v5, 1, v4
	v_lshrrev_b32_e32 v6, 2, v4
	v_and_b32_e32 v2, 3, v2
	v_and_b32_e32 v0, 32, v0
	v_bfe_i32 v3, v3, 0, 16
	v_and_b32_e32 v5, 24, v5
	v_and_b32_e32 v6, 4, v6
	v_and_or_b32 v2, v4, s76, v2
	v_or3_b32 v2, v2, v6, v5
	v_add_lshl_u32 v3, v0, v3, 1
	v_add_u32_e32 v1, 0x2000, v1
	v_lshl_add_u32 v152, v2, 9, v3
	v_ashrrev_i32_e32 v2, 31, v1
	v_lshrrev_b32_e32 v2, 22, v2
	v_add_u32_e32 v2, v1, v2
	v_ashrrev_i32_e32 v2, 10, v2
	v_lshl_add_u32 v0, v4, 11, v3
	v_mul_i32_i24_e32 v3, 0x400, v2
	v_sub_u32_e32 v1, v1, v3
	v_lshrrev_b32_e32 v3, 4, v1
	v_bitop3_b32 v1, v3, v1, 32 bitop3:0x6c
	v_ashrrev_i32_e32 v4, 31, v1
	v_lshrrev_b32_e32 v4, 26, v4
	v_lshlrev_b32_e32 v3, 3, v2
	v_add_u32_e32 v4, v1, v4
	v_readfirstlane_b32 s2, v14
	v_and_b32_e32 v3, -16, v3
	v_ashrrev_i32_e32 v5, 6, v4
	v_and_b32_e32 v4, 0xc0, v4
	v_add_u32_e32 v3, v5, v3
	v_sub_u32_e32 v1, v1, v4
	s_ashr_i32 s19, s2, 6
	v_lshlrev_b32_e32 v2, 5, v2
	v_ashrrev_i16_sdwa v1, v184, sext(v1) dst_sel:DWORD dst_unused:UNUSED_PAD src0_sel:DWORD src1_sel:BYTE_0
	v_lshlrev_b32_e32 v4, 1, v3
	v_lshrrev_b32_e32 v6, 2, v3
	v_and_b32_e32 v5, 3, v5
	s_lshl_b32 s85, s19, 10
	v_and_b32_e32 v2, 32, v2
	v_bfe_i32 v1, v1, 0, 16
	v_and_b32_e32 v4, 24, v4
	v_and_b32_e32 v6, 4, v6
	v_and_or_b32 v5, v3, s76, v5
	s_add_i32 s88, s85, 0
	v_or3_b32 v4, v5, v6, v4
	v_add_lshl_u32 v1, v2, v1, 1
	s_add_i32 m0, s88, 0x10000
	v_lshl_add_u32 v4, v4, 9, v1
	global_load_lds_dwordx4 v152, s[26:27]
	s_add_i32 m0, s88, 0x12000
	s_ashr_i32 s3, s2, 8
	global_load_lds_dwordx4 v4, s[26:27]
	s_mov_b32 m0, s88
	s_add_i32 s89, s88, 0x2000
	v_lshl_add_u32 v2, v3, 11, v1
	global_load_lds_dwordx4 v0, s[24:25]
	s_mov_b32 m0, s89
	s_add_u32 s28, s26, 0x10000
	global_load_lds_dwordx4 v2, s[24:25]
	s_addc_u32 s29, s27, 0
	s_add_i32 m0, s88, 0x14000
	v_mov_b32_e32 v5, v153
	global_load_lds_dwordx4 v152, s[28:29]
	s_add_i32 m0, s88, 0x16000
	v_mov_b32_e32 v1, v153
	global_load_lds_dwordx4 v4, s[28:29]
	s_add_u32 s28, s24, 0x40000
	s_addc_u32 s29, s25, 0
	s_add_i32 s87, s88, 0x4000
	s_mov_b32 m0, s87
	s_add_i32 s83, s88, 0x6000
	global_load_lds_dwordx4 v0, s[28:29]
	s_mov_b32 m0, s83
	v_mov_b32_e32 v3, v153
	global_load_lds_dwordx4 v2, s[28:29]
	v_lshl_add_u64 v[12:13], s[26:27], 0, v[152:153]
	v_lshl_add_u64 v[10:11], s[26:27], 0, v[4:5]
	v_lshl_add_u64 v[6:7], s[24:25], 0, v[0:1]
	s_cmp_eq_u32 s3, 1
	v_lshl_add_u64 v[8:9], s[24:25], 0, v[2:3]
	s_cbranch_scc0 .LBB0_657
	s_barrier
